# rw_task<2> step loop unrolled x4 (fewer address updates); otherwise same as previous version
# speedup vs baseline: 1.0299x; 1.0120x over previous
; #define LAS __attribute__((address_space(3)))
; template <int R>
; __device__ __forceinline__ void rw_task(const Params& p, LAS unsigned char* shm, const int tid, const int s, const int d, const int h, const int half) {
;     ...
;             for (int ti = 0; ti < ntiles; ++ti) {
;                 const LAS float* ib = inb + (ti & 1) * RW_INF; LAS float* ob = outb + (ti & 1) * RW_OUTF;
;                 LAS float* ow0 = j == 0 ? ob + row0 : outb + 2 * RW_OUTF + l; LAS float* ow1 = j == 0 ? ob + row1 : outb + 2 * RW_OUTF + 64 + l; const int omask = j == 0 ? -1 : 0;
; #pragma unroll 2
;                 for (int st = 0; st < TT; ++st) {
;                     const LAS float* sb = ib + st * RW_STRIDE;
;                     f32x2 ww[4], kk[4], bb[4], kc[4], wr[4];
;                     { const f32x4 a = *(const LAS f32x4*)(sb + 8 * j), b = *(const LAS f32x4*)(sb + 8 * j + 4); ww[0] = (f32x2){a[0], a[1]}; ww[1] = (f32x2){a[2], a[3]}; ww[2] = (f32x2){b[0], b[1]}; ww[3] = (f32x2){b[2], b[3]}; }
;                     { const f32x4 a = *(const LAS f32x4*)(sb + 64 + 8 * j), b = *(const LAS f32x4*)(sb + 64 + 8 * j + 4); kk[0] = (f32x2){a[0], a[1]}; kk[1] = (f32x2){a[2], a[3]}; kk[2] = (f32x2){b[0], b[1]}; kk[3] = (f32x2){b[2], b[3]}; }
;                     { const f32x4 a = *(const LAS f32x4*)(sb + 128 + 8 * j), b = *(const LAS f32x4*)(sb + 128 + 8 * j + 4); bb[0] = (f32x2){a[0], a[1]}; bb[1] = (f32x2){a[2], a[3]}; bb[2] = (f32x2){b[0], b[1]}; bb[3] = (f32x2){b[2], b[3]}; }
;                     { const f32x4 a = *(const LAS f32x4*)(sb + 192 + 8 * j), b = *(const LAS f32x4*)(sb + 192 + 8 * j + 4); kc[0] = (f32x2){a[0], a[1]}; kc[1] = (f32x2){a[2], a[3]}; kc[2] = (f32x2){b[0], b[1]}; kc[3] = (f32x2){b[2], b[3]}; }
;                     { const f32x4 a = *(const LAS f32x4*)(sb + 256 + 8 * j), b = *(const LAS f32x4*)(sb + 256 + 8 * j + 4); wr[0] = (f32x2){a[0], a[1]}; wr[1] = (f32x2){a[2], a[3]}; wr[2] = (f32x2){b[0], b[1]}; wr[3] = (f32x2){b[2], b[3]}; }
;                     const float v0 = sb[320 + row0], v1 = R == 2 ? sb[320 + row1] : 0.f; const f32x2 sc = *(const LAS f32x2*)(sb + 384); const float br = sc[0], kr = sc[1];
;                     if constexpr (R == 2) {
;                     f32x2 pa0 = s0[0] * kk[0], px0 = s0[0] * wr[0], pa1 = s1[0] * kk[0], px1 = s1[0] * wr[0];
; #pragma unroll
.LBB0_205:
	v_cndmask_b32_e64 v1, 0, 1, s[0:1]
	s_mov_b32 s5, 0xc200
	v_mul_lo_u32 v24, v1, s5
	s_and_b32 s5, s4, 1
	v_lshl_add_u32 v26, s5, 13, v18
	v_cndmask_b32_e32 v25, v19, v26, vcc
	v_add_u32_e32 v26, 32, v26
	v_add_u32_e32 v1, 0, v24
	v_add_u32_e32 v23, v21, v24
	v_add_u32_e32 v24, v22, v24
	v_cndmask_b32_e32 v26, v20, v26, vcc
	s_mov_b32 s5, 64
	s_mov_b32 s6, 0
	v_mov_b32_e32 v130, v24
	v_mov_b32_e32 v132, v23
	v_mov_b32_e32 v133, v1
	v_mov_b32_e32 v156, v25
	v_mov_b32_e32 v157, v26
	ds_read_b128 v[28:31], v130 offset:0
	ds_read_b128 v[32:35], v130 offset:16
	ds_read_b128 v[36:39], v130 offset:256
	ds_read_b128 v[40:43], v130 offset:272
	ds_read_b128 v[44:47], v130 offset:512
	ds_read_b128 v[48:51], v130 offset:528
	ds_read_b128 v[52:55], v130 offset:768
	ds_read_b128 v[56:59], v130 offset:784
	ds_read_b128 v[60:63], v130 offset:1024
	ds_read_b128 v[64:67], v130 offset:1040
	ds_read2_b32 v[68:69], v23 offset0:0 offset1:8
	ds_read_b64 v[70:71], v133 offset:1536
	s_waitcnt lgkmcnt(2)
.Lrw2_step:
	ds_read_b128 v[74:77], v130 offset:1552
	ds_read_b128 v[78:81], v130 offset:1568
	ds_read_b128 v[82:85], v130 offset:1808
	ds_read_b128 v[86:89], v130 offset:1824
	ds_read_b128 v[92:95], v130 offset:2064
	ds_read_b128 v[96:99], v130 offset:2080
	ds_read_b128 v[100:103], v130 offset:2320
	ds_read_b128 v[104:107], v130 offset:2336
	ds_read_b128 v[108:111], v130 offset:2576
	ds_read_b128 v[112:115], v130 offset:2592
	ds_read_b32 v116, v132 offset:1552
	ds_read_b32 v117, v132 offset:1584
	ds_read_b64 v[118:119], v133 offset:3088
	s_waitcnt lgkmcnt(13)
	v_pk_mul_f32 v[120:121], v[10:11], v[36:37]
	v_pk_mul_f32 v[124:125], v[2:3], v[36:37]
	v_pk_mul_f32 v[122:123], v[10:11], v[60:61]
	v_pk_mul_f32 v[126:127], v[2:3], v[60:61]
	v_pk_fma_f32 v[120:121], v[12:13], v[38:39], v[120:121]
	v_pk_fma_f32 v[124:125], v[4:5], v[38:39], v[124:125]
	v_pk_fma_f32 v[122:123], v[12:13], v[62:63], v[122:123]
	v_pk_fma_f32 v[126:127], v[4:5], v[62:63], v[126:127]
	v_pk_fma_f32 v[120:121], v[14:15], v[40:41], v[120:121]
	v_pk_fma_f32 v[124:125], v[6:7], v[40:41], v[124:125]
	v_pk_fma_f32 v[122:123], v[14:15], v[64:65], v[122:123]
	v_pk_fma_f32 v[126:127], v[6:7], v[64:65], v[126:127]
	v_pk_fma_f32 v[120:121], v[16:17], v[42:43], v[120:121]
	v_pk_fma_f32 v[124:125], v[8:9], v[42:43], v[124:125]
	v_pk_fma_f32 v[122:123], v[16:17], v[66:67], v[122:123]
	v_pk_fma_f32 v[126:127], v[8:9], v[66:67], v[126:127]
	v_pk_mul_f32 v[136:137], v[10:11], v[28:29]
	v_pk_mul_f32 v[148:149], v[2:3], v[28:29]
	v_add_f32_e32 v120, v120, v121
	v_add_f32_e32 v124, v124, v125
	v_add_f32_e32 v122, v122, v123
	v_add_f32_e32 v126, v126, v127
	v_pk_mul_f32 v[138:139], v[12:13], v[30:31]
	v_pk_mul_f32 v[150:151], v[4:5], v[30:31]
	v_add_f32_dpp v120, v120, v120 quad_perm:[1,0,3,2] row_mask:0xf bank_mask:0xf bound_ctrl:1
	v_add_f32_dpp v124, v124, v124 quad_perm:[1,0,3,2] row_mask:0xf bank_mask:0xf bound_ctrl:1
	v_pk_mul_f32 v[140:141], v[14:15], v[32:33]
	v_pk_mul_f32 v[152:153], v[6:7], v[32:33]
	v_add_f32_dpp v122, v122, v122 quad_perm:[1,0,3,2] row_mask:0xf bank_mask:0xf bound_ctrl:1
	v_add_f32_dpp v126, v126, v126 quad_perm:[1,0,3,2] row_mask:0xf bank_mask:0xf bound_ctrl:1
	v_pk_mul_f32 v[142:143], v[16:17], v[34:35]
	v_pk_mul_f32 v[154:155], v[8:9], v[34:35]
	v_add_f32_dpp v120, v120, v120 quad_perm:[2,3,0,1] row_mask:0xf bank_mask:0xf bound_ctrl:1
	v_add_f32_dpp v124, v124, v124 quad_perm:[2,3,0,1] row_mask:0xf bank_mask:0xf bound_ctrl:1
	v_pk_fma_f32 v[136:137], v[52:53], v[68:69], v[136:137] op_sel_hi:[1,0,1]
	v_pk_fma_f32 v[148:149], v[52:53], v[68:69], v[148:149] op_sel:[0,1,0] op_sel_hi:[1,1,1]
	v_add_f32_dpp v122, v122, v122 quad_perm:[2,3,0,1] row_mask:0xf bank_mask:0xf bound_ctrl:1
	v_add_f32_dpp v126, v126, v126 quad_perm:[2,3,0,1] row_mask:0xf bank_mask:0xf bound_ctrl:1
	v_pk_fma_f32 v[138:139], v[54:55], v[68:69], v[138:139] op_sel_hi:[1,0,1]
	v_pk_fma_f32 v[150:151], v[54:55], v[68:69], v[150:151] op_sel:[0,1,0] op_sel_hi:[1,1,1]
	v_add_f32_dpp v120, v120, v120 row_half_mirror row_mask:0xf bank_mask:0xf bound_ctrl:1
	v_add_f32_dpp v124, v124, v124 row_half_mirror row_mask:0xf bank_mask:0xf bound_ctrl:1
	v_pk_fma_f32 v[140:141], v[56:57], v[68:69], v[140:141] op_sel_hi:[1,0,1]
	v_pk_fma_f32 v[152:153], v[56:57], v[68:69], v[152:153] op_sel:[0,1,0] op_sel_hi:[1,1,1]
	v_add_f32_dpp v122, v122, v122 row_half_mirror row_mask:0xf bank_mask:0xf bound_ctrl:1
	v_add_f32_dpp v126, v126, v126 row_half_mirror row_mask:0xf bank_mask:0xf bound_ctrl:1
	v_pk_fma_f32 v[142:143], v[58:59], v[68:69], v[142:143] op_sel_hi:[1,0,1]
	v_pk_fma_f32 v[154:155], v[58:59], v[68:69], v[154:155] op_sel:[0,1,0] op_sel_hi:[1,1,1]
	v_mul_f32_e32 v144, v68, v71
	v_mul_f32_e32 v145, v69, v71
	v_pk_fma_f32 v[10:11], v[44:45], v[120:121], v[136:137] op_sel_hi:[1,0,1] neg_lo:[0,1,0] neg_hi:[0,1,0]
	v_pk_fma_f32 v[2:3], v[44:45], v[124:125], v[148:149] op_sel_hi:[1,0,1] neg_lo:[0,1,0] neg_hi:[0,1,0]
	v_fma_f32 v144, -v120, v70, v144
	v_fma_f32 v145, -v124, v70, v145
	v_pk_fma_f32 v[12:13], v[46:47], v[120:121], v[138:139] op_sel_hi:[1,0,1] neg_lo:[0,1,0] neg_hi:[0,1,0]
	v_pk_fma_f32 v[4:5], v[46:47], v[124:125], v[150:151] op_sel_hi:[1,0,1] neg_lo:[0,1,0] neg_hi:[0,1,0]
	v_add_f32_e32 v128, v122, v144
	v_add_f32_e32 v129, v126, v145
	v_pk_fma_f32 v[14:15], v[48:49], v[120:121], v[140:141] op_sel_hi:[1,0,1] neg_lo:[0,1,0] neg_hi:[0,1,0]
	v_pk_fma_f32 v[6:7], v[48:49], v[124:125], v[152:153] op_sel_hi:[1,0,1] neg_lo:[0,1,0] neg_hi:[0,1,0]
	ds_write_b32 v156, v128 offset:0
	ds_write_b32 v157, v129 offset:0
	v_pk_fma_f32 v[16:17], v[50:51], v[120:121], v[142:143] op_sel_hi:[1,0,1] neg_lo:[0,1,0] neg_hi:[0,1,0]
	v_pk_fma_f32 v[8:9], v[50:51], v[124:125], v[154:155] op_sel_hi:[1,0,1] neg_lo:[0,1,0] neg_hi:[0,1,0]
	ds_read_b128 v[28:31], v130 offset:3104
	ds_read_b128 v[32:35], v130 offset:3120
	ds_read_b128 v[36:39], v130 offset:3360
	ds_read_b128 v[40:43], v130 offset:3376
	ds_read_b128 v[44:47], v130 offset:3616
	ds_read_b128 v[48:51], v130 offset:3632
	ds_read_b128 v[52:55], v130 offset:3872
	ds_read_b128 v[56:59], v130 offset:3888
	ds_read_b128 v[60:63], v130 offset:4128
	ds_read_b128 v[64:67], v130 offset:4144
	ds_read_b32 v68, v132 offset:3104
	ds_read_b32 v69, v132 offset:3136
	ds_read_b64 v[70:71], v133 offset:4640
	s_waitcnt lgkmcnt(13)
; #define LAS __attribute__((address_space(3)))
; template <int R>
; __device__ __forceinline__ void rw_task(const Params& p, LAS unsigned char* shm, const int tid, const int s, const int d, const int h, const int half) {
;     ...
;                 for (int st = 0; st < TT; ++st) {
;                     const LAS float* sb = ib + st * RW_STRIDE;
;                     f32x2 ww[4], kk[4], bb[4], kc[4], wr[4];
;                     { const f32x4 a = *(const LAS f32x4*)(sb + 8 * j), b = *(const LAS f32x4*)(sb + 8 * j + 4); ww[0] = (f32x2){a[0], a[1]}; ww[1] = (f32x2){a[2], a[3]}; ww[2] = (f32x2){b[0], b[1]}; ww[3] = (f32x2){b[2], b[3]}; }
;                     { const f32x4 a = *(const LAS f32x4*)(sb + 64 + 8 * j), b = *(const LAS f32x4*)(sb + 64 + 8 * j + 4); kk[0] = (f32x2){a[0], a[1]}; kk[1] = (f32x2){a[2], a[3]}; kk[2] = (f32x2){b[0], b[1]}; kk[3] = (f32x2){b[2], b[3]}; }
;                     { const f32x4 a = *(const LAS f32x4*)(sb + 128 + 8 * j), b = *(const LAS f32x4*)(sb + 128 + 8 * j + 4); bb[0] = (f32x2){a[0], a[1]}; bb[1] = (f32x2){a[2], a[3]}; bb[2] = (f32x2){b[0], b[1]}; bb[3] = (f32x2){b[2], b[3]}; }
;                     { const f32x4 a = *(const LAS f32x4*)(sb + 192 + 8 * j), b = *(const LAS f32x4*)(sb + 192 + 8 * j + 4); kc[0] = (f32x2){a[0], a[1]}; kc[1] = (f32x2){a[2], a[3]}; kc[2] = (f32x2){b[0], b[1]}; kc[3] = (f32x2){b[2], b[3]}; }
;                     { const f32x4 a = *(const LAS f32x4*)(sb + 256 + 8 * j), b = *(const LAS f32x4*)(sb + 256 + 8 * j + 4); wr[0] = (f32x2){a[0], a[1]}; wr[1] = (f32x2){a[2], a[3]}; wr[2] = (f32x2){b[0], b[1]}; wr[3] = (f32x2){b[2], b[3]}; }
;                     const float v0 = sb[320 + row0], v1 = R == 2 ? sb[320 + row1] : 0.f; const f32x2 sc = *(const LAS f32x2*)(sb + 384); const float br = sc[0], kr = sc[1];
;                     if constexpr (R == 2) {
;                     f32x2 pa0 = s0[0] * kk[0], px0 = s0[0] * wr[0], pa1 = s1[0] * kk[0], px1 = s1[0] * wr[0];
; #pragma unroll
;                     for (int e = 1; e < 4; ++e) { pa0 += s0[e] * kk[e]; px0 += s0[e] * wr[e]; pa1 += s1[e] * kk[e]; px1 += s1[e] * wr[e]; }
;                     const float sa0 = red8(pa0[0] + pa0[1]), x0 = red8(px0[0] + px0[1]), sa1 = red8(pa1[0] + pa1[1]), x1 = red8(px1[0] + px1[1]);
;                     const float o0 = x0 - sa0 * br + v0 * kr, o1 = x1 - sa1 * br + v1 * kr;
	v_pk_mul_f32 v[120:121], v[10:11], v[82:83]
	v_pk_mul_f32 v[124:125], v[2:3], v[82:83]
	v_pk_mul_f32 v[122:123], v[10:11], v[108:109]
	v_pk_mul_f32 v[126:127], v[2:3], v[108:109]
	v_pk_fma_f32 v[120:121], v[12:13], v[84:85], v[120:121]
	v_pk_fma_f32 v[124:125], v[4:5], v[84:85], v[124:125]
	v_pk_fma_f32 v[122:123], v[12:13], v[110:111], v[122:123]
	v_pk_fma_f32 v[126:127], v[4:5], v[110:111], v[126:127]
	v_pk_fma_f32 v[120:121], v[14:15], v[86:87], v[120:121]
	v_pk_fma_f32 v[124:125], v[6:7], v[86:87], v[124:125]
	v_pk_fma_f32 v[122:123], v[14:15], v[112:113], v[122:123]
	v_pk_fma_f32 v[126:127], v[6:7], v[112:113], v[126:127]
	v_pk_fma_f32 v[120:121], v[16:17], v[88:89], v[120:121]
	v_pk_fma_f32 v[124:125], v[8:9], v[88:89], v[124:125]
	v_pk_fma_f32 v[122:123], v[16:17], v[114:115], v[122:123]
	v_pk_fma_f32 v[126:127], v[8:9], v[114:115], v[126:127]
	v_pk_mul_f32 v[136:137], v[10:11], v[74:75]
	v_pk_mul_f32 v[148:149], v[2:3], v[74:75]
	v_add_f32_e32 v120, v120, v121
	v_add_f32_e32 v124, v124, v125
	v_add_f32_e32 v122, v122, v123
	v_add_f32_e32 v126, v126, v127
	v_pk_mul_f32 v[138:139], v[12:13], v[76:77]
	v_pk_mul_f32 v[150:151], v[4:5], v[76:77]
	v_add_f32_dpp v120, v120, v120 quad_perm:[1,0,3,2] row_mask:0xf bank_mask:0xf bound_ctrl:1
	v_add_f32_dpp v124, v124, v124 quad_perm:[1,0,3,2] row_mask:0xf bank_mask:0xf bound_ctrl:1
	v_pk_mul_f32 v[140:141], v[14:15], v[78:79]
	v_pk_mul_f32 v[152:153], v[6:7], v[78:79]
	v_add_f32_dpp v122, v122, v122 quad_perm:[1,0,3,2] row_mask:0xf bank_mask:0xf bound_ctrl:1
	v_add_f32_dpp v126, v126, v126 quad_perm:[1,0,3,2] row_mask:0xf bank_mask:0xf bound_ctrl:1
	v_pk_mul_f32 v[142:143], v[16:17], v[80:81]
	v_pk_mul_f32 v[154:155], v[8:9], v[80:81]
	v_add_f32_dpp v120, v120, v120 quad_perm:[2,3,0,1] row_mask:0xf bank_mask:0xf bound_ctrl:1
	v_add_f32_dpp v124, v124, v124 quad_perm:[2,3,0,1] row_mask:0xf bank_mask:0xf bound_ctrl:1
	v_pk_fma_f32 v[136:137], v[100:101], v[116:117], v[136:137] op_sel_hi:[1,0,1]
	v_pk_fma_f32 v[148:149], v[100:101], v[116:117], v[148:149] op_sel:[0,1,0] op_sel_hi:[1,1,1]
	v_add_f32_dpp v122, v122, v122 quad_perm:[2,3,0,1] row_mask:0xf bank_mask:0xf bound_ctrl:1
	v_add_f32_dpp v126, v126, v126 quad_perm:[2,3,0,1] row_mask:0xf bank_mask:0xf bound_ctrl:1
	v_pk_fma_f32 v[138:139], v[102:103], v[116:117], v[138:139] op_sel_hi:[1,0,1]
	v_pk_fma_f32 v[150:151], v[102:103], v[116:117], v[150:151] op_sel:[0,1,0] op_sel_hi:[1,1,1]
	v_add_f32_dpp v120, v120, v120 row_half_mirror row_mask:0xf bank_mask:0xf bound_ctrl:1
	v_add_f32_dpp v124, v124, v124 row_half_mirror row_mask:0xf bank_mask:0xf bound_ctrl:1
	v_pk_fma_f32 v[140:141], v[104:105], v[116:117], v[140:141] op_sel_hi:[1,0,1]
	v_pk_fma_f32 v[152:153], v[104:105], v[116:117], v[152:153] op_sel:[0,1,0] op_sel_hi:[1,1,1]
	v_add_f32_dpp v122, v122, v122 row_half_mirror row_mask:0xf bank_mask:0xf bound_ctrl:1
	v_add_f32_dpp v126, v126, v126 row_half_mirror row_mask:0xf bank_mask:0xf bound_ctrl:1
	v_pk_fma_f32 v[142:143], v[106:107], v[116:117], v[142:143] op_sel_hi:[1,0,1]
	v_pk_fma_f32 v[154:155], v[106:107], v[116:117], v[154:155] op_sel:[0,1,0] op_sel_hi:[1,1,1]
	v_mul_f32_e32 v144, v116, v119
	v_mul_f32_e32 v145, v117, v119
	v_pk_fma_f32 v[10:11], v[92:93], v[120:121], v[136:137] op_sel_hi:[1,0,1] neg_lo:[0,1,0] neg_hi:[0,1,0]
	v_pk_fma_f32 v[2:3], v[92:93], v[124:125], v[148:149] op_sel_hi:[1,0,1] neg_lo:[0,1,0] neg_hi:[0,1,0]
	v_fma_f32 v144, -v120, v118, v144
	v_fma_f32 v145, -v124, v118, v145
	v_pk_fma_f32 v[12:13], v[94:95], v[120:121], v[138:139] op_sel_hi:[1,0,1] neg_lo:[0,1,0] neg_hi:[0,1,0]
	v_pk_fma_f32 v[4:5], v[94:95], v[124:125], v[150:151] op_sel_hi:[1,0,1] neg_lo:[0,1,0] neg_hi:[0,1,0]
	v_add_f32_e32 v128, v122, v144
	v_add_f32_e32 v129, v126, v145
	v_pk_fma_f32 v[14:15], v[96:97], v[120:121], v[140:141] op_sel_hi:[1,0,1] neg_lo:[0,1,0] neg_hi:[0,1,0]
	v_pk_fma_f32 v[6:7], v[96:97], v[124:125], v[152:153] op_sel_hi:[1,0,1] neg_lo:[0,1,0] neg_hi:[0,1,0]
	ds_write_b32 v156, v128 offset:256
	ds_write_b32 v157, v129 offset:256
	v_pk_fma_f32 v[16:17], v[98:99], v[120:121], v[142:143] op_sel_hi:[1,0,1] neg_lo:[0,1,0] neg_hi:[0,1,0]
	v_pk_fma_f32 v[8:9], v[98:99], v[124:125], v[154:155] op_sel_hi:[1,0,1] neg_lo:[0,1,0] neg_hi:[0,1,0]
	ds_read_b128 v[74:77], v130 offset:4656
	ds_read_b128 v[78:81], v130 offset:4672
	ds_read_b128 v[82:85], v130 offset:4912
	ds_read_b128 v[86:89], v130 offset:4928
	ds_read_b128 v[92:95], v130 offset:5168
	ds_read_b128 v[96:99], v130 offset:5184
	ds_read_b128 v[100:103], v130 offset:5424
	ds_read_b128 v[104:107], v130 offset:5440
	ds_read_b128 v[108:111], v130 offset:5680
	ds_read_b128 v[112:115], v130 offset:5696
	ds_read_b32 v116, v132 offset:4656
	ds_read_b32 v117, v132 offset:4688
	ds_read_b64 v[118:119], v133 offset:6192
	s_waitcnt lgkmcnt(13)
; #define LAS __attribute__((address_space(3)))
; template <int R>
; __device__ __forceinline__ void rw_task(const Params& p, LAS unsigned char* shm, const int tid, const int s, const int d, const int h, const int half) {
;     ...
;                 for (int st = 0; st < TT; ++st) {
;                     const LAS float* sb = ib + st * RW_STRIDE;
;                     f32x2 ww[4], kk[4], bb[4], kc[4], wr[4];
;                     { const f32x4 a = *(const LAS f32x4*)(sb + 8 * j), b = *(const LAS f32x4*)(sb + 8 * j + 4); ww[0] = (f32x2){a[0], a[1]}; ww[1] = (f32x2){a[2], a[3]}; ww[2] = (f32x2){b[0], b[1]}; ww[3] = (f32x2){b[2], b[3]}; }
;                     { const f32x4 a = *(const LAS f32x4*)(sb + 64 + 8 * j), b = *(const LAS f32x4*)(sb + 64 + 8 * j + 4); kk[0] = (f32x2){a[0], a[1]}; kk[1] = (f32x2){a[2], a[3]}; kk[2] = (f32x2){b[0], b[1]}; kk[3] = (f32x2){b[2], b[3]}; }
;                     { const f32x4 a = *(const LAS f32x4*)(sb + 128 + 8 * j), b = *(const LAS f32x4*)(sb + 128 + 8 * j + 4); bb[0] = (f32x2){a[0], a[1]}; bb[1] = (f32x2){a[2], a[3]}; bb[2] = (f32x2){b[0], b[1]}; bb[3] = (f32x2){b[2], b[3]}; }
;                     { const f32x4 a = *(const LAS f32x4*)(sb + 192 + 8 * j), b = *(const LAS f32x4*)(sb + 192 + 8 * j + 4); kc[0] = (f32x2){a[0], a[1]}; kc[1] = (f32x2){a[2], a[3]}; kc[2] = (f32x2){b[0], b[1]}; kc[3] = (f32x2){b[2], b[3]}; }
;                     { const f32x4 a = *(const LAS f32x4*)(sb + 256 + 8 * j), b = *(const LAS f32x4*)(sb + 256 + 8 * j + 4); wr[0] = (f32x2){a[0], a[1]}; wr[1] = (f32x2){a[2], a[3]}; wr[2] = (f32x2){b[0], b[1]}; wr[3] = (f32x2){b[2], b[3]}; }
;                     const float v0 = sb[320 + row0], v1 = R == 2 ? sb[320 + row1] : 0.f; const f32x2 sc = *(const LAS f32x2*)(sb + 384); const float br = sc[0], kr = sc[1];
;                     if constexpr (R == 2) {
;                     f32x2 pa0 = s0[0] * kk[0], px0 = s0[0] * wr[0], pa1 = s1[0] * kk[0], px1 = s1[0] * wr[0];
; #pragma unroll
;                     for (int e = 1; e < 4; ++e) { pa0 += s0[e] * kk[e]; px0 += s0[e] * wr[e]; pa1 += s1[e] * kk[e]; px1 += s1[e] * wr[e]; }
;                     const float sa0 = red8(pa0[0] + pa0[1]), x0 = red8(px0[0] + px0[1]), sa1 = red8(pa1[0] + pa1[1]), x1 = red8(px1[0] + px1[1]);
;                     const float o0 = x0 - sa0 * br + v0 * kr, o1 = x1 - sa1 * br + v1 * kr;
	v_pk_mul_f32 v[120:121], v[10:11], v[36:37]
	v_pk_mul_f32 v[124:125], v[2:3], v[36:37]
	v_pk_mul_f32 v[122:123], v[10:11], v[60:61]
	v_pk_mul_f32 v[126:127], v[2:3], v[60:61]
	v_pk_fma_f32 v[120:121], v[12:13], v[38:39], v[120:121]
	v_pk_fma_f32 v[124:125], v[4:5], v[38:39], v[124:125]
	v_pk_fma_f32 v[122:123], v[12:13], v[62:63], v[122:123]
	v_pk_fma_f32 v[126:127], v[4:5], v[62:63], v[126:127]
	v_pk_fma_f32 v[120:121], v[14:15], v[40:41], v[120:121]
	v_pk_fma_f32 v[124:125], v[6:7], v[40:41], v[124:125]
	v_pk_fma_f32 v[122:123], v[14:15], v[64:65], v[122:123]
	v_pk_fma_f32 v[126:127], v[6:7], v[64:65], v[126:127]
	v_pk_fma_f32 v[120:121], v[16:17], v[42:43], v[120:121]
	v_pk_fma_f32 v[124:125], v[8:9], v[42:43], v[124:125]
	v_pk_fma_f32 v[122:123], v[16:17], v[66:67], v[122:123]
	v_pk_fma_f32 v[126:127], v[8:9], v[66:67], v[126:127]
	v_pk_mul_f32 v[136:137], v[10:11], v[28:29]
	v_pk_mul_f32 v[148:149], v[2:3], v[28:29]
	v_add_f32_e32 v120, v120, v121
	v_add_f32_e32 v124, v124, v125
	v_add_f32_e32 v122, v122, v123
	v_add_f32_e32 v126, v126, v127
	v_pk_mul_f32 v[138:139], v[12:13], v[30:31]
	v_pk_mul_f32 v[150:151], v[4:5], v[30:31]
	v_add_f32_dpp v120, v120, v120 quad_perm:[1,0,3,2] row_mask:0xf bank_mask:0xf bound_ctrl:1
	v_add_f32_dpp v124, v124, v124 quad_perm:[1,0,3,2] row_mask:0xf bank_mask:0xf bound_ctrl:1
	v_pk_mul_f32 v[140:141], v[14:15], v[32:33]
	v_pk_mul_f32 v[152:153], v[6:7], v[32:33]
	v_add_f32_dpp v122, v122, v122 quad_perm:[1,0,3,2] row_mask:0xf bank_mask:0xf bound_ctrl:1
	v_add_f32_dpp v126, v126, v126 quad_perm:[1,0,3,2] row_mask:0xf bank_mask:0xf bound_ctrl:1
	v_pk_mul_f32 v[142:143], v[16:17], v[34:35]
	v_pk_mul_f32 v[154:155], v[8:9], v[34:35]
	v_add_f32_dpp v120, v120, v120 quad_perm:[2,3,0,1] row_mask:0xf bank_mask:0xf bound_ctrl:1
	v_add_f32_dpp v124, v124, v124 quad_perm:[2,3,0,1] row_mask:0xf bank_mask:0xf bound_ctrl:1
	v_pk_fma_f32 v[136:137], v[52:53], v[68:69], v[136:137] op_sel_hi:[1,0,1]
	v_pk_fma_f32 v[148:149], v[52:53], v[68:69], v[148:149] op_sel:[0,1,0] op_sel_hi:[1,1,1]
	v_add_f32_dpp v122, v122, v122 quad_perm:[2,3,0,1] row_mask:0xf bank_mask:0xf bound_ctrl:1
	v_add_f32_dpp v126, v126, v126 quad_perm:[2,3,0,1] row_mask:0xf bank_mask:0xf bound_ctrl:1
	v_pk_fma_f32 v[138:139], v[54:55], v[68:69], v[138:139] op_sel_hi:[1,0,1]
	v_pk_fma_f32 v[150:151], v[54:55], v[68:69], v[150:151] op_sel:[0,1,0] op_sel_hi:[1,1,1]
	v_add_f32_dpp v120, v120, v120 row_half_mirror row_mask:0xf bank_mask:0xf bound_ctrl:1
	v_add_f32_dpp v124, v124, v124 row_half_mirror row_mask:0xf bank_mask:0xf bound_ctrl:1
	v_pk_fma_f32 v[140:141], v[56:57], v[68:69], v[140:141] op_sel_hi:[1,0,1]
	v_pk_fma_f32 v[152:153], v[56:57], v[68:69], v[152:153] op_sel:[0,1,0] op_sel_hi:[1,1,1]
	v_add_f32_dpp v122, v122, v122 row_half_mirror row_mask:0xf bank_mask:0xf bound_ctrl:1
	v_add_f32_dpp v126, v126, v126 row_half_mirror row_mask:0xf bank_mask:0xf bound_ctrl:1
	v_pk_fma_f32 v[142:143], v[58:59], v[68:69], v[142:143] op_sel_hi:[1,0,1]
	v_pk_fma_f32 v[154:155], v[58:59], v[68:69], v[154:155] op_sel:[0,1,0] op_sel_hi:[1,1,1]
	v_mul_f32_e32 v144, v68, v71
	v_mul_f32_e32 v145, v69, v71
	v_pk_fma_f32 v[10:11], v[44:45], v[120:121], v[136:137] op_sel_hi:[1,0,1] neg_lo:[0,1,0] neg_hi:[0,1,0]
	v_pk_fma_f32 v[2:3], v[44:45], v[124:125], v[148:149] op_sel_hi:[1,0,1] neg_lo:[0,1,0] neg_hi:[0,1,0]
	v_fma_f32 v144, -v120, v70, v144
	v_fma_f32 v145, -v124, v70, v145
	v_pk_fma_f32 v[12:13], v[46:47], v[120:121], v[138:139] op_sel_hi:[1,0,1] neg_lo:[0,1,0] neg_hi:[0,1,0]
	v_pk_fma_f32 v[4:5], v[46:47], v[124:125], v[150:151] op_sel_hi:[1,0,1] neg_lo:[0,1,0] neg_hi:[0,1,0]
	v_add_f32_e32 v128, v122, v144
	v_add_f32_e32 v129, v126, v145
	v_pk_fma_f32 v[14:15], v[48:49], v[120:121], v[140:141] op_sel_hi:[1,0,1] neg_lo:[0,1,0] neg_hi:[0,1,0]
	v_pk_fma_f32 v[6:7], v[48:49], v[124:125], v[152:153] op_sel_hi:[1,0,1] neg_lo:[0,1,0] neg_hi:[0,1,0]
	ds_write_b32 v156, v128 offset:512
	ds_write_b32 v157, v129 offset:512
	v_pk_fma_f32 v[16:17], v[50:51], v[120:121], v[142:143] op_sel_hi:[1,0,1] neg_lo:[0,1,0] neg_hi:[0,1,0]
	v_pk_fma_f32 v[8:9], v[50:51], v[124:125], v[154:155] op_sel_hi:[1,0,1] neg_lo:[0,1,0] neg_hi:[0,1,0]
	ds_read_b128 v[28:31], v130 offset:6208
	ds_read_b128 v[32:35], v130 offset:6224
	ds_read_b128 v[36:39], v130 offset:6464
	ds_read_b128 v[40:43], v130 offset:6480
	ds_read_b128 v[44:47], v130 offset:6720
	ds_read_b128 v[48:51], v130 offset:6736
	ds_read_b128 v[52:55], v130 offset:6976
	ds_read_b128 v[56:59], v130 offset:6992
	ds_read_b128 v[60:63], v130 offset:7232
	ds_read_b128 v[64:67], v130 offset:7248
	ds_read_b32 v68, v132 offset:6208
	ds_read_b32 v69, v132 offset:6240
	ds_read_b64 v[70:71], v133 offset:7744
	s_waitcnt lgkmcnt(13)
; #define LAS __attribute__((address_space(3)))
; template <int R>
; __device__ __forceinline__ void rw_task(const Params& p, LAS unsigned char* shm, const int tid, const int s, const int d, const int h, const int half) {
;     ...
;             for (int ti = 0; ti < ntiles; ++ti) {
;                 const LAS float* ib = inb + (ti & 1) * RW_INF; LAS float* ob = outb + (ti & 1) * RW_OUTF;
;                 LAS float* ow0 = j == 0 ? ob + row0 : outb + 2 * RW_OUTF + l; LAS float* ow1 = j == 0 ? ob + row1 : outb + 2 * RW_OUTF + 64 + l; const int omask = j == 0 ? -1 : 0;
; #pragma unroll 2
;                 for (int st = 0; st < TT; ++st) {
;                     const LAS float* sb = ib + st * RW_STRIDE;
;                     f32x2 ww[4], kk[4], bb[4], kc[4], wr[4];
;                     { const f32x4 a = *(const LAS f32x4*)(sb + 8 * j), b = *(const LAS f32x4*)(sb + 8 * j + 4); ww[0] = (f32x2){a[0], a[1]}; ww[1] = (f32x2){a[2], a[3]}; ww[2] = (f32x2){b[0], b[1]}; ww[3] = (f32x2){b[2], b[3]}; }
;                     { const f32x4 a = *(const LAS f32x4*)(sb + 64 + 8 * j), b = *(const LAS f32x4*)(sb + 64 + 8 * j + 4); kk[0] = (f32x2){a[0], a[1]}; kk[1] = (f32x2){a[2], a[3]}; kk[2] = (f32x2){b[0], b[1]}; kk[3] = (f32x2){b[2], b[3]}; }
;                     { const f32x4 a = *(const LAS f32x4*)(sb + 128 + 8 * j), b = *(const LAS f32x4*)(sb + 128 + 8 * j + 4); bb[0] = (f32x2){a[0], a[1]}; bb[1] = (f32x2){a[2], a[3]}; bb[2] = (f32x2){b[0], b[1]}; bb[3] = (f32x2){b[2], b[3]}; }
;                     { const f32x4 a = *(const LAS f32x4*)(sb + 192 + 8 * j), b = *(const LAS f32x4*)(sb + 192 + 8 * j + 4); kc[0] = (f32x2){a[0], a[1]}; kc[1] = (f32x2){a[2], a[3]}; kc[2] = (f32x2){b[0], b[1]}; kc[3] = (f32x2){b[2], b[3]}; }
;                     { const f32x4 a = *(const LAS f32x4*)(sb + 256 + 8 * j), b = *(const LAS f32x4*)(sb + 256 + 8 * j + 4); wr[0] = (f32x2){a[0], a[1]}; wr[1] = (f32x2){a[2], a[3]}; wr[2] = (f32x2){b[0], b[1]}; wr[3] = (f32x2){b[2], b[3]}; }
;                     const float v0 = sb[320 + row0], v1 = R == 2 ? sb[320 + row1] : 0.f; const f32x2 sc = *(const LAS f32x2*)(sb + 384); const float br = sc[0], kr = sc[1];
;                     if constexpr (R == 2) {
;                     f32x2 pa0 = s0[0] * kk[0], px0 = s0[0] * wr[0], pa1 = s1[0] * kk[0], px1 = s1[0] * wr[0];
; #pragma unroll
	v_pk_mul_f32 v[120:121], v[10:11], v[82:83]
	v_pk_mul_f32 v[124:125], v[2:3], v[82:83]
	v_pk_mul_f32 v[122:123], v[10:11], v[108:109]
	v_pk_mul_f32 v[126:127], v[2:3], v[108:109]
	v_pk_fma_f32 v[120:121], v[12:13], v[84:85], v[120:121]
	v_pk_fma_f32 v[124:125], v[4:5], v[84:85], v[124:125]
	v_pk_fma_f32 v[122:123], v[12:13], v[110:111], v[122:123]
	v_pk_fma_f32 v[126:127], v[4:5], v[110:111], v[126:127]
	v_pk_fma_f32 v[120:121], v[14:15], v[86:87], v[120:121]
	v_pk_fma_f32 v[124:125], v[6:7], v[86:87], v[124:125]
	v_pk_fma_f32 v[122:123], v[14:15], v[112:113], v[122:123]
	v_pk_fma_f32 v[126:127], v[6:7], v[112:113], v[126:127]
	v_pk_fma_f32 v[120:121], v[16:17], v[88:89], v[120:121]
	v_pk_fma_f32 v[124:125], v[8:9], v[88:89], v[124:125]
	v_pk_fma_f32 v[122:123], v[16:17], v[114:115], v[122:123]
	v_pk_fma_f32 v[126:127], v[8:9], v[114:115], v[126:127]
	v_pk_mul_f32 v[136:137], v[10:11], v[74:75]
	v_pk_mul_f32 v[148:149], v[2:3], v[74:75]
	v_add_f32_e32 v120, v120, v121
	v_add_f32_e32 v124, v124, v125
	v_add_f32_e32 v122, v122, v123
	v_add_f32_e32 v126, v126, v127
	v_pk_mul_f32 v[138:139], v[12:13], v[76:77]
	v_pk_mul_f32 v[150:151], v[4:5], v[76:77]
	v_add_f32_dpp v120, v120, v120 quad_perm:[1,0,3,2] row_mask:0xf bank_mask:0xf bound_ctrl:1
	v_add_f32_dpp v124, v124, v124 quad_perm:[1,0,3,2] row_mask:0xf bank_mask:0xf bound_ctrl:1
	v_pk_mul_f32 v[140:141], v[14:15], v[78:79]
	v_pk_mul_f32 v[152:153], v[6:7], v[78:79]
	v_add_f32_dpp v122, v122, v122 quad_perm:[1,0,3,2] row_mask:0xf bank_mask:0xf bound_ctrl:1
	v_add_f32_dpp v126, v126, v126 quad_perm:[1,0,3,2] row_mask:0xf bank_mask:0xf bound_ctrl:1
	v_pk_mul_f32 v[142:143], v[16:17], v[80:81]
	v_pk_mul_f32 v[154:155], v[8:9], v[80:81]
	v_add_f32_dpp v120, v120, v120 quad_perm:[2,3,0,1] row_mask:0xf bank_mask:0xf bound_ctrl:1
	v_add_f32_dpp v124, v124, v124 quad_perm:[2,3,0,1] row_mask:0xf bank_mask:0xf bound_ctrl:1
	v_pk_fma_f32 v[136:137], v[100:101], v[116:117], v[136:137] op_sel_hi:[1,0,1]
	v_pk_fma_f32 v[148:149], v[100:101], v[116:117], v[148:149] op_sel:[0,1,0] op_sel_hi:[1,1,1]
	v_add_f32_dpp v122, v122, v122 quad_perm:[2,3,0,1] row_mask:0xf bank_mask:0xf bound_ctrl:1
	v_add_f32_dpp v126, v126, v126 quad_perm:[2,3,0,1] row_mask:0xf bank_mask:0xf bound_ctrl:1
	v_pk_fma_f32 v[138:139], v[102:103], v[116:117], v[138:139] op_sel_hi:[1,0,1]
	v_pk_fma_f32 v[150:151], v[102:103], v[116:117], v[150:151] op_sel:[0,1,0] op_sel_hi:[1,1,1]
	v_add_f32_dpp v120, v120, v120 row_half_mirror row_mask:0xf bank_mask:0xf bound_ctrl:1
	v_add_f32_dpp v124, v124, v124 row_half_mirror row_mask:0xf bank_mask:0xf bound_ctrl:1
	v_pk_fma_f32 v[140:141], v[104:105], v[116:117], v[140:141] op_sel_hi:[1,0,1]
	v_pk_fma_f32 v[152:153], v[104:105], v[116:117], v[152:153] op_sel:[0,1,0] op_sel_hi:[1,1,1]
	v_add_f32_dpp v122, v122, v122 row_half_mirror row_mask:0xf bank_mask:0xf bound_ctrl:1
	v_add_f32_dpp v126, v126, v126 row_half_mirror row_mask:0xf bank_mask:0xf bound_ctrl:1
	v_pk_fma_f32 v[142:143], v[106:107], v[116:117], v[142:143] op_sel_hi:[1,0,1]
	v_pk_fma_f32 v[154:155], v[106:107], v[116:117], v[154:155] op_sel:[0,1,0] op_sel_hi:[1,1,1]
	v_mul_f32_e32 v144, v116, v119
	v_mul_f32_e32 v145, v117, v119
	v_pk_fma_f32 v[10:11], v[92:93], v[120:121], v[136:137] op_sel_hi:[1,0,1] neg_lo:[0,1,0] neg_hi:[0,1,0]
	v_pk_fma_f32 v[2:3], v[92:93], v[124:125], v[148:149] op_sel_hi:[1,0,1] neg_lo:[0,1,0] neg_hi:[0,1,0]
	v_fma_f32 v144, -v120, v118, v144
	v_fma_f32 v145, -v124, v118, v145
	v_pk_fma_f32 v[12:13], v[94:95], v[120:121], v[138:139] op_sel_hi:[1,0,1] neg_lo:[0,1,0] neg_hi:[0,1,0]
	v_pk_fma_f32 v[4:5], v[94:95], v[124:125], v[150:151] op_sel_hi:[1,0,1] neg_lo:[0,1,0] neg_hi:[0,1,0]
	v_add_f32_e32 v128, v122, v144
	v_add_f32_e32 v129, v126, v145
	v_pk_fma_f32 v[14:15], v[96:97], v[120:121], v[140:141] op_sel_hi:[1,0,1] neg_lo:[0,1,0] neg_hi:[0,1,0]
	v_pk_fma_f32 v[6:7], v[96:97], v[124:125], v[152:153] op_sel_hi:[1,0,1] neg_lo:[0,1,0] neg_hi:[0,1,0]
	ds_write_b32 v156, v128 offset:768
	ds_write_b32 v157, v129 offset:768
	v_pk_fma_f32 v[16:17], v[98:99], v[120:121], v[142:143] op_sel_hi:[1,0,1] neg_lo:[0,1,0] neg_hi:[0,1,0]
	v_pk_fma_f32 v[8:9], v[98:99], v[124:125], v[154:155] op_sel_hi:[1,0,1] neg_lo:[0,1,0] neg_hi:[0,1,0]
	v_add_u32_e32 v130, 0x1840, v130
	v_add_u32_e32 v132, 0x1840, v132
	v_add_u32_e32 v133, 0x1840, v133
	v_add_u32_e32 v156, 0x400, v156
	v_add_u32_e32 v157, 0x400, v157
	s_add_i32 s6, s6, 1
	s_cmp_eq_u32 s6, 8
	s_cbranch_scc0 .Lrw2_step
	s_add_i32 s4, s4, 1
	s_xor_b64 s[0:1], s[0:1], -1
	s_cmpk_eq_i32 s4, 0x80
	s_waitcnt lgkmcnt(0)
	s_barrier
	s_cbranch_scc0 .LBB0_205
